# filler priority 3 plus diff-latent QK MFMAs issued back-to-back with all four K fragments read at the loop top
# baseline (speedup 1.0000x reference)
.LBB0_427:
	s_setprio 0
	s_bitcmp1_b32 s18, 0
	s_cselect_b32 s98, 0x4800, 0
	v_or_b32_e32 v210, s98, v166
	v_add_u32_e32 v210, v210, v171
	ds_read_b128 v[4:7], v210
	ds_read_b128 v[8:11], v210 offset:32
	ds_read_b128 v[178:181], v210 offset:4608
	ds_read_b128 v[182:185], v210 offset:4640
	s_cmpk_gt_u32 s18, 0x41
	s_cbranch_scc1 .LBB0_431
	s_mov_b64 s[8:9], 0x100
	s_cmp_lt_u32 s18, 2
	s_mov_b64 s[4:5], s[0:1]
	s_mov_b64 s[6:7], s[2:3]
	s_cbranch_scc1 .LBB0_430
	s_lshl_b64 s[4:5], s[56:57], 7
	s_add_u32 s6, s15, s4
	s_addc_u32 s7, s16, s5
	s_lshl_b64 s[4:5], s[56:57], 1
	s_add_u32 s4, s13, s4
	s_addc_u32 s5, s14, s5
	s_mov_b64 s[8:9], 0x1000

.LBB0_431:
	s_bitcmp1_b32 s18, 0
	s_cselect_b32 s4, 0x4800, 0
	v_or_b32_e32 v0, s4, v166
	v_add_u32_e32 v210, v0, v171
	s_mov_b32 s5, 0xff800000
	s_waitcnt lgkmcnt(3)
	v_mfma_f32_32x32x16_bf16 v[96:111], v[4:7], v[112:115], 0
	s_waitcnt lgkmcnt(1)
	v_mfma_f32_32x32x16_bf16 v[80:95], v[178:181], v[112:115], 0
	v_mfma_f32_32x32x16_bf16 v[96:111], v[8:11], v[116:119], v[96:111]
	s_waitcnt lgkmcnt(0)
	v_mfma_f32_32x32x16_bf16 v[80:95], v[182:185], v[116:119], v[80:95]
	ds_read_b128 v[244:247], v210 offset:64
	ds_read_b128 v[214:217], v210 offset:96
	ds_read_b128 v[228:231], v210 offset:4672
	v_add3_u32 v248, s4, v235, v171
	v_add_u32_e32 v249, 0x3000, v248
	v_add_u32_e32 v248, 0x2000, v248
	ds_read2_b64 v[144:147], v249 offset0:196 offset1:198
	ds_read2_b64 v[148:151], v248 offset0:136 offset1:138
	ds_read2_b64 v[152:155], v249 offset0:200 offset1:202
	ds_read2_b64 v[156:159], v248 offset0:140 offset1:142
	ds_read2_b64 v[160:163], v249 offset0:204 offset1:206
	s_nop 3
	v_max3_f32 v0, v96, s5, v97
	v_max3_f32 v0, v0, v98, v99
	v_max3_f32 v0, v0, v100, v101
	v_max3_f32 v0, v0, v102, v103
	v_max3_f32 v0, v0, v104, v105
	v_max3_f32 v0, v0, v106, v107
	v_max3_f32 v0, v0, v108, v109
	v_max3_f32 v0, v0, v110, v111
	v_max3_f32 v0, v0, v80, v81
	v_max3_f32 v0, v0, v82, v83
	v_max3_f32 v0, v0, v84, v85
	v_max3_f32 v0, v0, v86, v87
	v_max3_f32 v0, v0, v88, v89
	v_max3_f32 v0, v0, v90, v91
	v_max3_f32 v0, v0, v92, v93
	v_max3_f32 v0, v0, v94, v95
	v_mul_f32_e32 v0, 0x3e8293ee, v0
	v_mov_b32_e32 v3, v0
	s_nop 1
	v_permlane32_swap_b32_e32 v3, v0
	s_nop 0
	v_max3_f32 v0, v2, v0, v3
	v_sub_f32_e32 v3, v2, v0
	v_exp_f32_e32 v14, v3
	v_cmp_neq_f32_e32 vcc, v0, v2
	s_cbranch_vccz .LBB0_433
	v_pk_mul_f32 v[62:63], v[62:63], v[14:15] op_sel_hi:[1,0]
	v_pk_mul_f32 v[60:61], v[60:61], v[14:15] op_sel_hi:[1,0]
	v_pk_mul_f32 v[58:59], v[58:59], v[14:15] op_sel_hi:[1,0]
	v_pk_mul_f32 v[56:57], v[56:57], v[14:15] op_sel_hi:[1,0]
	v_pk_mul_f32 v[54:55], v[54:55], v[14:15] op_sel_hi:[1,0]
	v_pk_mul_f32 v[52:53], v[52:53], v[14:15] op_sel_hi:[1,0]
	v_pk_mul_f32 v[50:51], v[50:51], v[14:15] op_sel_hi:[1,0]
	v_pk_mul_f32 v[48:49], v[48:49], v[14:15] op_sel_hi:[1,0]
	v_pk_mul_f32 v[30:31], v[30:31], v[14:15] op_sel_hi:[1,0]
	v_pk_mul_f32 v[28:29], v[28:29], v[14:15] op_sel_hi:[1,0]
	v_pk_mul_f32 v[26:27], v[26:27], v[14:15] op_sel_hi:[1,0]
	v_pk_mul_f32 v[24:25], v[24:25], v[14:15] op_sel_hi:[1,0]
	v_pk_mul_f32 v[22:23], v[22:23], v[14:15] op_sel_hi:[1,0]
	v_pk_mul_f32 v[20:21], v[20:21], v[14:15] op_sel_hi:[1,0]
	v_pk_mul_f32 v[18:19], v[18:19], v[14:15] op_sel_hi:[1,0]
	v_pk_mul_f32 v[16:17], v[16:17], v[14:15] op_sel_hi:[1,0]
